# GLA cumdecay: hoist the 8 serialized gate-row loads into one burst (both inlined copies)
# speedup vs baseline: 1.0092x; 1.0092x over previous
.LBB0_768:
	s_bfe_u32 s15, s14, 0x20007
	s_lshl_b32 s16, s15, 6
	v_or_b32_e32 v0, s16, v196
	s_ashr_i32 s4, s14, 9
	v_lshlrev_b32_e32 v0, 2, v0
	v_mov_b32_e32 v1, v32
	s_ashr_i32 s5, s4, 31
	v_lshl_add_u64 v[2:3], s[56:57], 0, v[0:1]
	s_lshl_b64 s[4:5], s[4:5], 13
	s_and_b32 s6, s12, 0x1fc0
	v_add_co_u32_e32 v4, vcc, s20, v2
	s_or_b32 s4, s4, s6
	s_nop 0
	v_addc_co_u32_e32 v5, vcc, 0, v3, vcc
	s_movk_i32 s6, 0x2000
	v_add_co_u32_e32 v6, vcc, s6, v2
	s_movk_i32 s6, 0x3000
	s_nop 0
	v_addc_co_u32_e32 v7, vcc, 0, v3, vcc
	v_add_co_u32_e32 v2, vcc, s6, v2
	global_load_dword v21, v0, s[56:57]
	global_load_dword v23, v0, s[56:57] offset:1024
	global_load_dword v20, v0, s[56:57] offset:2048
	global_load_dword v18, v0, s[56:57] offset:3072
	v_addc_co_u32_e32 v3, vcc, 0, v3, vcc
	global_load_dword v22, v[6:7], off offset:-4096
	global_load_dword v19, v[4:5], off offset:1024
	global_load_dword v17, v[4:5], off offset:2048
	global_load_dword v16, v[4:5], off offset:3072
	global_load_dword v14, v[6:7], off
	global_load_dword v15, v[6:7], off offset:1024
	global_load_dword v13, v[6:7], off offset:2048
	global_load_dword v11, v[6:7], off offset:3072
	global_load_dword v12, v[2:3], off
	global_load_dword v10, v[2:3], off offset:1024
	global_load_dword v9, v[2:3], off offset:2048
	global_load_dword v8, v[2:3], off offset:3072
	global_load_dword v24, v0, s[58:59]
	v_lshl_add_u64 v[2:3], s[4:5], 0, v[42:43]
	v_mov_b64_e32 v[0:1], s[80:81]
	s_movk_i32 s17, 0x2cb0
	v_mad_u64_u32 v[4:5], s[6:7], v2, s17, v[0:1]
	v_mad_i32_i24 v5, v3, s17, v5
	v_add_co_u32_e32 v2, vcc, s20, v4
	s_mov_b64 s[26:27], 0x1c90
	s_nop 0
	v_addc_co_u32_e32 v3, vcc, 0, v5, vcc
	v_lshl_add_u64 v[6:7], v[4:5], 0, s[26:27]
	v_lshl_add_u64 v[216:217], s[4:5], 0, v[42:43]
	v_mad_u64_u32 v[218:219], s[6:7], v216, s17, v[0:1]
	v_mad_i32_i24 v219, v217, s17, v219
	v_lshl_add_u64 v[218:219], v[218:219], 0, s[26:27]
	global_load_dwordx4 v[100:103], v[218:219], off
	global_load_dwordx4 v[104:107], v[218:219], off offset:16
	v_lshl_add_u64 v[220:221], s[4:5], 0, v[44:45]
	v_mad_u64_u32 v[222:223], s[6:7], v220, s17, v[0:1]
	v_mad_i32_i24 v223, v221, s17, v223
	v_lshl_add_u64 v[222:223], v[222:223], 0, s[26:27]
	global_load_dwordx4 v[108:111], v[222:223], off
	global_load_dwordx4 v[112:115], v[222:223], off offset:16
	v_lshl_add_u64 v[216:217], s[4:5], 0, v[46:47]
	v_mad_u64_u32 v[218:219], s[6:7], v216, s17, v[0:1]
	v_mad_i32_i24 v219, v217, s17, v219
	v_lshl_add_u64 v[218:219], v[218:219], 0, s[26:27]
	global_load_dwordx4 v[116:119], v[218:219], off
	global_load_dwordx4 v[120:123], v[218:219], off offset:16
	v_lshl_add_u64 v[220:221], s[4:5], 0, v[48:49]
	v_mad_u64_u32 v[222:223], s[6:7], v220, s17, v[0:1]
	v_mad_i32_i24 v223, v221, s17, v223
	v_lshl_add_u64 v[222:223], v[222:223], 0, s[26:27]
	global_load_dwordx4 v[124:127], v[222:223], off
	global_load_dwordx4 v[128:131], v[222:223], off offset:16
	v_lshl_add_u64 v[216:217], s[4:5], 0, v[50:51]
	v_mad_u64_u32 v[218:219], s[6:7], v216, s17, v[0:1]
	v_mad_i32_i24 v219, v217, s17, v219
	v_lshl_add_u64 v[218:219], v[218:219], 0, s[26:27]
	global_load_dwordx4 v[132:135], v[218:219], off
	global_load_dwordx4 v[136:139], v[218:219], off offset:16
	v_lshl_add_u64 v[220:221], s[4:5], 0, v[52:53]
	v_mad_u64_u32 v[222:223], s[6:7], v220, s17, v[0:1]
	v_mad_i32_i24 v223, v221, s17, v223
	v_lshl_add_u64 v[222:223], v[222:223], 0, s[26:27]
	global_load_dwordx4 v[140:143], v[222:223], off
	global_load_dwordx4 v[144:147], v[222:223], off offset:16
	v_lshl_add_u64 v[216:217], s[4:5], 0, v[54:55]
	v_mad_u64_u32 v[218:219], s[6:7], v216, s17, v[0:1]
	v_mad_i32_i24 v219, v217, s17, v219
	v_lshl_add_u64 v[218:219], v[218:219], 0, s[26:27]
	global_load_dwordx4 v[200:203], v[218:219], off
	global_load_dwordx4 v[204:207], v[218:219], off offset:16
	v_lshl_add_u64 v[220:221], s[4:5], 0, v[56:57]
	v_mad_u64_u32 v[222:223], s[6:7], v220, s17, v[0:1]
	v_mad_i32_i24 v223, v221, s17, v223
	v_lshl_add_u64 v[222:223], v[222:223], 0, s[26:27]
	global_load_dwordx4 v[208:211], v[222:223], off
	global_load_dwordx4 v[212:215], v[222:223], off offset:16
	s_waitcnt vmcnt(0)
	v_mov_b64_e32 v[2:3], v[100:101]
	v_mov_b64_e32 v[4:5], v[102:103]
	s_nop 0
	v_mov_b64_e32 v[26:27], v[104:105]
	v_mov_b64_e32 v[28:29], v[106:107]
	s_mov_b32 s18, 0xbfb8aa3b
	s_mov_b32 s19, 0x800000
	s_mov_b32 s21, 0x3f317217
	s_mov_b32 s22, 0x7f800000
	s_mov_b32 s6, 0x3d800000
	v_add_u32_e32 v25, 0x400, v95
	s_waitcnt vmcnt(1)
	v_lshlrev_b32_e32 v6, 16, v2
	v_and_b32_e32 v2, 0xffff0000, v2
	v_mul_f32_e32 v2, v23, v2
	v_fmac_f32_e32 v2, v21, v6
	v_lshlrev_b32_e32 v6, 16, v3
	v_fmac_f32_e32 v2, v20, v6
	v_and_b32_e32 v3, 0xffff0000, v3
	v_fmac_f32_e32 v2, v18, v3
	v_lshlrev_b32_e32 v3, 16, v4
	v_fmac_f32_e32 v2, v22, v3
	v_and_b32_e32 v3, 0xffff0000, v4
	v_fmac_f32_e32 v2, v19, v3
	v_lshlrev_b32_e32 v3, 16, v5
	v_fmac_f32_e32 v2, v17, v3
	v_and_b32_e32 v3, 0xffff0000, v5
	s_waitcnt vmcnt(0)
	v_and_b32_e32 v4, 0xffff0000, v26
	v_fmac_f32_e32 v2, v16, v3
	v_lshlrev_b32_e32 v3, 16, v26
	v_mul_f32_e32 v4, v15, v4
	v_fmac_f32_e32 v4, v14, v3
	v_lshlrev_b32_e32 v3, 16, v27
	v_fmac_f32_e32 v4, v13, v3
	v_and_b32_e32 v3, 0xffff0000, v27
	v_fmac_f32_e32 v4, v11, v3
	v_lshlrev_b32_e32 v3, 16, v28
	v_fmac_f32_e32 v4, v12, v3
	v_and_b32_e32 v3, 0xffff0000, v28
	v_fmac_f32_e32 v4, v10, v3
	v_lshlrev_b32_e32 v3, 16, v29
	v_fmac_f32_e32 v4, v9, v3
	v_and_b32_e32 v3, 0xffff0000, v29
	v_add_f32_e32 v2, v24, v2
	v_fmac_f32_e32 v4, v8, v3
	v_add_f32_e32 v2, v2, v4
	v_min_f32_e32 v3, 0, v2
	v_mul_f32_e64 v2, |v2|, s18
	v_exp_f32_e32 v2, v2
	s_nop 0
	v_add_f32_e32 v2, 1.0, v2
	v_cmp_gt_f32_e32 vcc, s19, v2
	s_nop 1
	v_cndmask_b32_e64 v4, 0, 32, vcc
	v_ldexp_f32 v2, v2, v4
	v_log_f32_e32 v2, v2
	s_nop 0
	v_mul_f32_e32 v4, 0x3f317217, v2
	v_fma_f32 v4, v2, s21, -v4
	v_fmac_f32_e32 v4, 0x3377d1cf, v2
	v_fmac_f32_e32 v4, 0x3f317217, v2
	v_cmp_lt_f32_e64 s[90:91], |v2|, s22
	s_nop 1
	v_cndmask_b32_e64 v2, v2, v4, s[90:91]
	v_cndmask_b32_e32 v4, 0, v195, vcc
	v_sub_f32_e32 v2, v2, v4
	v_sub_f32_e32 v2, v3, v2
	v_lshl_add_u64 v[4:5], s[4:5], 0, v[44:45]
	v_fma_f32 v3, v2, s6, 0
	v_mad_u64_u32 v[6:7], s[6:7], v4, s17, v[0:1]
	v_mad_i32_i24 v7, v5, s17, v7
	v_add_co_u32_e32 v4, vcc, s20, v6
	ds_write_b32 v94, v3
	v_lshl_add_u64 v[26:27], v[6:7], 0, s[26:27]
	v_addc_co_u32_e32 v5, vcc, 0, v7, vcc
	v_mov_b64_e32 v[4:5], v[108:109]
	v_mov_b64_e32 v[6:7], v[110:111]
	s_nop 0
	v_mov_b64_e32 v[26:27], v[112:113]
	v_mov_b64_e32 v[28:29], v[114:115]
	s_waitcnt vmcnt(1)
	v_lshlrev_b32_e32 v2, 16, v4
	v_and_b32_e32 v4, 0xffff0000, v4
	v_mul_f32_e32 v4, v23, v4
	v_fmac_f32_e32 v4, v21, v2
	v_lshlrev_b32_e32 v2, 16, v5
	v_fmac_f32_e32 v4, v20, v2
	v_and_b32_e32 v2, 0xffff0000, v5
	v_fmac_f32_e32 v4, v18, v2
	v_lshlrev_b32_e32 v2, 16, v6
	v_fmac_f32_e32 v4, v22, v2
	v_and_b32_e32 v2, 0xffff0000, v6
	v_fmac_f32_e32 v4, v19, v2
	v_lshlrev_b32_e32 v2, 16, v7
	v_fmac_f32_e32 v4, v17, v2
	v_and_b32_e32 v2, 0xffff0000, v7
	v_fmac_f32_e32 v4, v16, v2
	s_waitcnt vmcnt(0)
	v_and_b32_e32 v5, 0xffff0000, v26
	v_add_f32_e32 v2, v24, v4
	v_lshlrev_b32_e32 v4, 16, v26
	v_mul_f32_e32 v5, v15, v5
	v_fmac_f32_e32 v5, v14, v4
	v_lshlrev_b32_e32 v4, 16, v27
	v_fmac_f32_e32 v5, v13, v4
	v_and_b32_e32 v4, 0xffff0000, v27
	v_fmac_f32_e32 v5, v11, v4
	v_lshlrev_b32_e32 v4, 16, v28
	v_fmac_f32_e32 v5, v12, v4
	v_and_b32_e32 v4, 0xffff0000, v28
	v_fmac_f32_e32 v5, v10, v4
	v_lshlrev_b32_e32 v4, 16, v29
	v_fmac_f32_e32 v5, v9, v4
	v_and_b32_e32 v4, 0xffff0000, v29
	v_fmac_f32_e32 v5, v8, v4
	v_add_f32_e32 v2, v2, v5
	v_min_f32_e32 v4, 0, v2
	v_mul_f32_e64 v2, |v2|, s18
	v_exp_f32_e32 v2, v2
	s_nop 0
	v_add_f32_e32 v2, 1.0, v2
	v_cmp_gt_f32_e32 vcc, s19, v2
	s_nop 1
	v_cndmask_b32_e64 v5, 0, 32, vcc
	v_ldexp_f32 v2, v2, v5
	v_log_f32_e32 v2, v2
	s_nop 0
	v_mul_f32_e32 v5, 0x3f317217, v2
	v_fma_f32 v5, v2, s21, -v5
	v_fmac_f32_e32 v5, 0x3377d1cf, v2
	v_fmac_f32_e32 v5, 0x3f317217, v2
	v_cmp_lt_f32_e64 s[90:91], |v2|, s22
	s_nop 1
	v_cndmask_b32_e64 v2, v2, v5, s[90:91]
	v_cndmask_b32_e32 v5, 0, v195, vcc
	v_sub_f32_e32 v2, v2, v5
	v_sub_f32_e32 v2, v4, v2
	v_lshl_add_u64 v[4:5], s[4:5], 0, v[46:47]
	v_mad_u64_u32 v[6:7], s[6:7], v4, s17, v[0:1]
	v_mad_i32_i24 v7, v5, s17, v7
	v_add_co_u32_e32 v4, vcc, s20, v6
	v_lshl_add_u64 v[26:27], v[6:7], 0, s[26:27]
	s_nop 0
	v_addc_co_u32_e32 v5, vcc, 0, v7, vcc
	v_mov_b64_e32 v[4:5], v[116:117]
	v_mov_b64_e32 v[6:7], v[118:119]
	s_nop 0
	v_mov_b64_e32 v[26:27], v[120:121]
	v_mov_b64_e32 v[28:29], v[122:123]
	v_fmac_f32_e32 v3, 0x3d800000, v2
	s_waitcnt vmcnt(1)
	v_lshlrev_b32_e32 v2, 16, v4
	v_and_b32_e32 v4, 0xffff0000, v4
	v_mul_f32_e32 v4, v23, v4
	v_fmac_f32_e32 v4, v21, v2
	v_lshlrev_b32_e32 v2, 16, v5
	v_fmac_f32_e32 v4, v20, v2
	v_and_b32_e32 v2, 0xffff0000, v5
	v_fmac_f32_e32 v4, v18, v2
	v_lshlrev_b32_e32 v2, 16, v6
	v_fmac_f32_e32 v4, v22, v2
	v_and_b32_e32 v2, 0xffff0000, v6
	v_fmac_f32_e32 v4, v19, v2
	v_lshlrev_b32_e32 v2, 16, v7
	v_fmac_f32_e32 v4, v17, v2
	v_and_b32_e32 v2, 0xffff0000, v7
	v_fmac_f32_e32 v4, v16, v2
	s_waitcnt vmcnt(0)
	v_and_b32_e32 v5, 0xffff0000, v26
	v_add_f32_e32 v2, v24, v4
	v_lshlrev_b32_e32 v4, 16, v26
	v_mul_f32_e32 v5, v15, v5
	v_fmac_f32_e32 v5, v14, v4
	v_lshlrev_b32_e32 v4, 16, v27
	v_fmac_f32_e32 v5, v13, v4
	v_and_b32_e32 v4, 0xffff0000, v27
	v_fmac_f32_e32 v5, v11, v4
	v_lshlrev_b32_e32 v4, 16, v28
	v_fmac_f32_e32 v5, v12, v4
	v_and_b32_e32 v4, 0xffff0000, v28
	v_fmac_f32_e32 v5, v10, v4
	v_lshlrev_b32_e32 v4, 16, v29
	v_fmac_f32_e32 v5, v9, v4
	v_and_b32_e32 v4, 0xffff0000, v29
	v_fmac_f32_e32 v5, v8, v4
	v_add_f32_e32 v2, v2, v5
	v_min_f32_e32 v4, 0, v2
	v_mul_f32_e64 v2, |v2|, s18
	v_exp_f32_e32 v2, v2
	s_nop 0
	v_add_f32_e32 v2, 1.0, v2
	v_cmp_gt_f32_e32 vcc, s19, v2
	s_nop 1
	v_cndmask_b32_e64 v5, 0, 32, vcc
	v_ldexp_f32 v2, v2, v5
	v_log_f32_e32 v2, v2
	s_nop 0
	v_mul_f32_e32 v5, 0x3f317217, v2
	v_fma_f32 v5, v2, s21, -v5
	v_fmac_f32_e32 v5, 0x3377d1cf, v2
	v_fmac_f32_e32 v5, 0x3f317217, v2
	v_cmp_lt_f32_e64 s[90:91], |v2|, s22
	s_nop 1
	v_cndmask_b32_e64 v2, v2, v5, s[90:91]
	v_cndmask_b32_e32 v5, 0, v195, vcc
	v_sub_f32_e32 v2, v2, v5
	v_sub_f32_e32 v2, v4, v2
	v_lshl_add_u64 v[4:5], s[4:5], 0, v[48:49]
	v_mad_u64_u32 v[6:7], s[6:7], v4, s17, v[0:1]
	v_fmamk_f32 v2, v2, 0x3d800000, v3
	v_mad_i32_i24 v7, v5, s17, v7
	v_add_co_u32_e32 v4, vcc, s20, v6
	ds_write2_b32 v95, v3, v2 offset1:65
	v_lshl_add_u64 v[26:27], v[6:7], 0, s[26:27]
	v_addc_co_u32_e32 v5, vcc, 0, v7, vcc
	v_mov_b64_e32 v[4:5], v[124:125]
	v_mov_b64_e32 v[6:7], v[126:127]
	s_nop 0
	v_mov_b64_e32 v[26:27], v[128:129]
	v_mov_b64_e32 v[28:29], v[130:131]
	s_waitcnt vmcnt(1)
	v_lshlrev_b32_e32 v3, 16, v4
	v_and_b32_e32 v4, 0xffff0000, v4
	v_mul_f32_e32 v4, v23, v4
	v_fmac_f32_e32 v4, v21, v3
	v_lshlrev_b32_e32 v3, 16, v5
	v_fmac_f32_e32 v4, v20, v3
	v_and_b32_e32 v3, 0xffff0000, v5
	v_fmac_f32_e32 v4, v18, v3
	v_lshlrev_b32_e32 v3, 16, v6
	v_fmac_f32_e32 v4, v22, v3
	v_and_b32_e32 v3, 0xffff0000, v6
	v_fmac_f32_e32 v4, v19, v3
	v_lshlrev_b32_e32 v3, 16, v7
	v_fmac_f32_e32 v4, v17, v3
	v_and_b32_e32 v3, 0xffff0000, v7
	v_fmac_f32_e32 v4, v16, v3
	s_waitcnt vmcnt(0)
	v_and_b32_e32 v5, 0xffff0000, v26
	v_add_f32_e32 v3, v24, v4
	v_lshlrev_b32_e32 v4, 16, v26
	v_mul_f32_e32 v5, v15, v5
	v_fmac_f32_e32 v5, v14, v4
	v_lshlrev_b32_e32 v4, 16, v27
	v_fmac_f32_e32 v5, v13, v4
	v_and_b32_e32 v4, 0xffff0000, v27
	v_fmac_f32_e32 v5, v11, v4
	v_lshlrev_b32_e32 v4, 16, v28
	v_fmac_f32_e32 v5, v12, v4
	v_and_b32_e32 v4, 0xffff0000, v28
	v_fmac_f32_e32 v5, v10, v4
	v_lshlrev_b32_e32 v4, 16, v29
	v_fmac_f32_e32 v5, v9, v4
	v_and_b32_e32 v4, 0xffff0000, v29
	v_fmac_f32_e32 v5, v8, v4
	v_add_f32_e32 v3, v3, v5
	v_min_f32_e32 v4, 0, v3
	v_mul_f32_e64 v3, |v3|, s18
	v_exp_f32_e32 v3, v3
	s_nop 0
	v_add_f32_e32 v3, 1.0, v3
	v_cmp_gt_f32_e32 vcc, s19, v3
	s_nop 1
	v_cndmask_b32_e64 v5, 0, 32, vcc
	v_ldexp_f32 v3, v3, v5
	v_log_f32_e32 v3, v3
	s_nop 0
	v_mul_f32_e32 v5, 0x3f317217, v3
	v_fma_f32 v5, v3, s21, -v5
	v_fmac_f32_e32 v5, 0x3377d1cf, v3
	v_fmac_f32_e32 v5, 0x3f317217, v3
	v_cmp_lt_f32_e64 s[90:91], |v3|, s22
	s_nop 1
	v_cndmask_b32_e64 v3, v3, v5, s[90:91]
	v_cndmask_b32_e32 v5, 0, v195, vcc
	v_sub_f32_e32 v3, v3, v5
	v_sub_f32_e32 v3, v4, v3
	v_lshl_add_u64 v[4:5], s[4:5], 0, v[50:51]
	v_mad_u64_u32 v[6:7], s[6:7], v4, s17, v[0:1]
	v_mad_i32_i24 v7, v5, s17, v7
	v_add_co_u32_e32 v4, vcc, s20, v6
	v_lshl_add_u64 v[26:27], v[6:7], 0, s[26:27]
	s_nop 0
	v_addc_co_u32_e32 v5, vcc, 0, v7, vcc
	v_mov_b64_e32 v[4:5], v[132:133]
	v_mov_b64_e32 v[6:7], v[134:135]
	s_nop 0
	v_mov_b64_e32 v[26:27], v[136:137]
	v_mov_b64_e32 v[28:29], v[138:139]
	v_fmac_f32_e32 v2, 0x3d800000, v3
	s_waitcnt vmcnt(1)
	v_lshlrev_b32_e32 v3, 16, v4
	v_and_b32_e32 v4, 0xffff0000, v4
	v_mul_f32_e32 v4, v23, v4
	v_fmac_f32_e32 v4, v21, v3
	v_lshlrev_b32_e32 v3, 16, v5
	v_fmac_f32_e32 v4, v20, v3
	v_and_b32_e32 v3, 0xffff0000, v5
	v_fmac_f32_e32 v4, v18, v3
	v_lshlrev_b32_e32 v3, 16, v6
	v_fmac_f32_e32 v4, v22, v3
	v_and_b32_e32 v3, 0xffff0000, v6
	v_fmac_f32_e32 v4, v19, v3
	v_lshlrev_b32_e32 v3, 16, v7
	v_fmac_f32_e32 v4, v17, v3
	v_and_b32_e32 v3, 0xffff0000, v7
	v_fmac_f32_e32 v4, v16, v3
	s_waitcnt vmcnt(0)
	v_and_b32_e32 v5, 0xffff0000, v26
	v_add_f32_e32 v3, v24, v4
	v_lshlrev_b32_e32 v4, 16, v26
	v_mul_f32_e32 v5, v15, v5
	v_fmac_f32_e32 v5, v14, v4
	v_lshlrev_b32_e32 v4, 16, v27
	v_fmac_f32_e32 v5, v13, v4
	v_and_b32_e32 v4, 0xffff0000, v27
	v_fmac_f32_e32 v5, v11, v4
	v_lshlrev_b32_e32 v4, 16, v28
	v_fmac_f32_e32 v5, v12, v4
	v_and_b32_e32 v4, 0xffff0000, v28
	v_fmac_f32_e32 v5, v10, v4
	v_lshlrev_b32_e32 v4, 16, v29
	v_fmac_f32_e32 v5, v9, v4
	v_and_b32_e32 v4, 0xffff0000, v29
	v_fmac_f32_e32 v5, v8, v4
	v_add_f32_e32 v3, v3, v5
	v_min_f32_e32 v4, 0, v3
	v_mul_f32_e64 v3, |v3|, s18
	v_exp_f32_e32 v3, v3
	s_nop 0
	v_add_f32_e32 v3, 1.0, v3
	v_cmp_gt_f32_e32 vcc, s19, v3
	s_nop 1
	v_cndmask_b32_e64 v5, 0, 32, vcc
	v_ldexp_f32 v3, v3, v5
	v_log_f32_e32 v3, v3
	s_nop 0
	v_mul_f32_e32 v5, 0x3f317217, v3
	v_fma_f32 v5, v3, s21, -v5
	v_fmac_f32_e32 v5, 0x3377d1cf, v3
	v_fmac_f32_e32 v5, 0x3f317217, v3
	v_cmp_lt_f32_e64 s[90:91], |v3|, s22
	s_nop 1
	v_cndmask_b32_e64 v3, v3, v5, s[90:91]
	v_cndmask_b32_e32 v5, 0, v195, vcc
	v_sub_f32_e32 v3, v3, v5
	v_sub_f32_e32 v3, v4, v3
	v_lshl_add_u64 v[4:5], s[4:5], 0, v[52:53]
	v_mad_u64_u32 v[6:7], s[6:7], v4, s17, v[0:1]
	v_fmamk_f32 v3, v3, 0x3d800000, v2
	v_mad_i32_i24 v7, v5, s17, v7
	v_add_co_u32_e32 v4, vcc, s20, v6
	ds_write2_b32 v95, v2, v3 offset0:130 offset1:195
	v_lshl_add_u64 v[26:27], v[6:7], 0, s[26:27]
	v_addc_co_u32_e32 v5, vcc, 0, v7, vcc
	v_mov_b64_e32 v[4:5], v[140:141]
	v_mov_b64_e32 v[6:7], v[142:143]
	s_nop 0
	v_mov_b64_e32 v[26:27], v[144:145]
	v_mov_b64_e32 v[28:29], v[146:147]
	s_waitcnt vmcnt(1)
	v_lshlrev_b32_e32 v2, 16, v4
	v_and_b32_e32 v4, 0xffff0000, v4
	v_mul_f32_e32 v4, v23, v4
	v_fmac_f32_e32 v4, v21, v2
	v_lshlrev_b32_e32 v2, 16, v5
	v_fmac_f32_e32 v4, v20, v2
	v_and_b32_e32 v2, 0xffff0000, v5
	v_fmac_f32_e32 v4, v18, v2
	v_lshlrev_b32_e32 v2, 16, v6
	v_fmac_f32_e32 v4, v22, v2
	v_and_b32_e32 v2, 0xffff0000, v6
	v_fmac_f32_e32 v4, v19, v2
	v_lshlrev_b32_e32 v2, 16, v7
	v_fmac_f32_e32 v4, v17, v2
	v_and_b32_e32 v2, 0xffff0000, v7
	v_fmac_f32_e32 v4, v16, v2
	s_waitcnt vmcnt(0)
	v_and_b32_e32 v5, 0xffff0000, v26
	v_add_f32_e32 v2, v24, v4
	v_lshlrev_b32_e32 v4, 16, v26
	v_mul_f32_e32 v5, v15, v5
	v_fmac_f32_e32 v5, v14, v4
	v_lshlrev_b32_e32 v4, 16, v27
	v_fmac_f32_e32 v5, v13, v4
	v_and_b32_e32 v4, 0xffff0000, v27
	v_fmac_f32_e32 v5, v11, v4
	v_lshlrev_b32_e32 v4, 16, v28
	v_fmac_f32_e32 v5, v12, v4
	v_and_b32_e32 v4, 0xffff0000, v28
	v_fmac_f32_e32 v5, v10, v4
	v_lshlrev_b32_e32 v4, 16, v29
	v_fmac_f32_e32 v5, v9, v4
	v_and_b32_e32 v4, 0xffff0000, v29
	v_fmac_f32_e32 v5, v8, v4
	v_add_f32_e32 v2, v2, v5
	v_min_f32_e32 v4, 0, v2
	v_mul_f32_e64 v2, |v2|, s18
	v_exp_f32_e32 v2, v2
	s_nop 0
	v_add_f32_e32 v2, 1.0, v2
	v_cmp_gt_f32_e32 vcc, s19, v2
	s_nop 1
	v_cndmask_b32_e64 v5, 0, 32, vcc
	v_ldexp_f32 v2, v2, v5
	v_log_f32_e32 v2, v2
	s_nop 0
	v_mul_f32_e32 v5, 0x3f317217, v2
	v_fma_f32 v5, v2, s21, -v5
	v_fmac_f32_e32 v5, 0x3377d1cf, v2
	v_fmac_f32_e32 v5, 0x3f317217, v2
	v_cmp_lt_f32_e64 s[90:91], |v2|, s22
	s_nop 1
	v_cndmask_b32_e64 v2, v2, v5, s[90:91]
	v_cndmask_b32_e32 v5, 0, v195, vcc
	v_sub_f32_e32 v2, v2, v5
	v_sub_f32_e32 v2, v4, v2
	v_lshl_add_u64 v[4:5], s[4:5], 0, v[54:55]
	v_mad_u64_u32 v[6:7], s[6:7], v4, s17, v[0:1]
	v_mad_i32_i24 v7, v5, s17, v7
	v_add_co_u32_e32 v4, vcc, s20, v6
	v_lshl_add_u64 v[26:27], v[6:7], 0, s[26:27]
	s_nop 0
	v_addc_co_u32_e32 v5, vcc, 0, v7, vcc
	v_mov_b64_e32 v[4:5], v[200:201]
	v_mov_b64_e32 v[6:7], v[202:203]
	s_nop 0
	v_mov_b64_e32 v[26:27], v[204:205]
	v_mov_b64_e32 v[28:29], v[206:207]
	v_fmac_f32_e32 v3, 0x3d800000, v2
	s_waitcnt vmcnt(1)
	v_lshlrev_b32_e32 v2, 16, v4
	v_and_b32_e32 v4, 0xffff0000, v4
	v_mul_f32_e32 v4, v23, v4
	v_fmac_f32_e32 v4, v21, v2
	v_lshlrev_b32_e32 v2, 16, v5
	v_fmac_f32_e32 v4, v20, v2
	v_and_b32_e32 v2, 0xffff0000, v5
	v_fmac_f32_e32 v4, v18, v2
	v_lshlrev_b32_e32 v2, 16, v6
	v_fmac_f32_e32 v4, v22, v2
	v_and_b32_e32 v2, 0xffff0000, v6
	v_fmac_f32_e32 v4, v19, v2
	v_lshlrev_b32_e32 v2, 16, v7
	v_fmac_f32_e32 v4, v17, v2
	v_and_b32_e32 v2, 0xffff0000, v7
	v_fmac_f32_e32 v4, v16, v2
	s_waitcnt vmcnt(0)
	v_and_b32_e32 v5, 0xffff0000, v26
	v_add_f32_e32 v2, v24, v4
	v_lshlrev_b32_e32 v4, 16, v26
	v_mul_f32_e32 v5, v15, v5
	v_fmac_f32_e32 v5, v14, v4
	v_lshlrev_b32_e32 v4, 16, v27
	v_fmac_f32_e32 v5, v13, v4
	v_and_b32_e32 v4, 0xffff0000, v27
	v_fmac_f32_e32 v5, v11, v4
	v_lshlrev_b32_e32 v4, 16, v28
	v_fmac_f32_e32 v5, v12, v4
	v_and_b32_e32 v4, 0xffff0000, v28
	v_fmac_f32_e32 v5, v10, v4
	v_lshlrev_b32_e32 v4, 16, v29
	v_fmac_f32_e32 v5, v9, v4
	v_and_b32_e32 v4, 0xffff0000, v29
	v_fmac_f32_e32 v5, v8, v4
	v_add_f32_e32 v2, v2, v5
	v_min_f32_e32 v4, 0, v2
	v_mul_f32_e64 v2, |v2|, s18
	v_exp_f32_e32 v2, v2
	s_nop 0
	v_add_f32_e32 v2, 1.0, v2
	v_cmp_gt_f32_e32 vcc, s19, v2
	s_nop 1
	v_cndmask_b32_e64 v5, 0, 32, vcc
	v_ldexp_f32 v2, v2, v5
	v_log_f32_e32 v2, v2
	s_nop 0
	v_mul_f32_e32 v5, 0x3f317217, v2
	v_fma_f32 v5, v2, s21, -v5
	v_fmac_f32_e32 v5, 0x3377d1cf, v2
	v_fmac_f32_e32 v5, 0x3f317217, v2
	v_cmp_lt_f32_e64 s[90:91], |v2|, s22
	s_nop 1
	v_cndmask_b32_e64 v2, v2, v5, s[90:91]
	v_cndmask_b32_e32 v5, 0, v195, vcc
	v_sub_f32_e32 v2, v2, v5
	v_sub_f32_e32 v2, v4, v2
	v_fmamk_f32 v26, v2, 0x3d800000, v3
	ds_write2_b32 v25, v3, v26 offset0:4 offset1:69
	v_lshl_add_u64 v[2:3], s[4:5], 0, v[56:57]
	v_mad_u64_u32 v[0:1], s[6:7], v2, s17, v[0:1]
	v_mad_i32_i24 v1, v3, s17, v1
	v_lshl_add_u64 v[4:5], v[0:1], 0, s[26:27]
	v_add_co_u32_e32 v0, vcc, s20, v0
	s_nop 1
	v_addc_co_u32_e32 v1, vcc, 0, v1, vcc
	v_mov_b64_e32 v[0:1], v[208:209]
	v_mov_b64_e32 v[2:3], v[210:211]
	s_nop 0
	v_mov_b64_e32 v[4:5], v[212:213]
	v_mov_b64_e32 v[6:7], v[214:215]
	s_waitcnt vmcnt(1)
	v_lshlrev_b32_e32 v27, 16, v0
	v_and_b32_e32 v0, 0xffff0000, v0
	v_mul_f32_e32 v0, v23, v0
	v_fmac_f32_e32 v0, v21, v27
	v_lshlrev_b32_e32 v21, 16, v1
	v_fmac_f32_e32 v0, v20, v21
	v_and_b32_e32 v1, 0xffff0000, v1
	v_fmac_f32_e32 v0, v18, v1
	v_lshlrev_b32_e32 v1, 16, v2
	v_fmac_f32_e32 v0, v22, v1
	v_and_b32_e32 v1, 0xffff0000, v2
	v_fmac_f32_e32 v0, v19, v1
	v_lshlrev_b32_e32 v1, 16, v3
	v_fmac_f32_e32 v0, v17, v1
	v_and_b32_e32 v1, 0xffff0000, v3
	s_waitcnt vmcnt(0)
	v_and_b32_e32 v2, 0xffff0000, v4
	v_fmac_f32_e32 v0, v16, v1
	v_lshlrev_b32_e32 v1, 16, v4
	v_mul_f32_e32 v2, v15, v2
	v_fmac_f32_e32 v2, v14, v1
	v_lshlrev_b32_e32 v1, 16, v5
	v_fmac_f32_e32 v2, v13, v1
	v_and_b32_e32 v1, 0xffff0000, v5
	v_fmac_f32_e32 v2, v11, v1
	v_lshlrev_b32_e32 v1, 16, v6
	v_fmac_f32_e32 v2, v12, v1
	v_and_b32_e32 v1, 0xffff0000, v6
	v_fmac_f32_e32 v2, v10, v1
	v_lshlrev_b32_e32 v1, 16, v7
	v_fmac_f32_e32 v2, v9, v1
	v_and_b32_e32 v1, 0xffff0000, v7
	v_add_f32_e32 v0, v24, v0
	v_fmac_f32_e32 v2, v8, v1
	v_add_f32_e32 v0, v0, v2
	v_min_f32_e32 v1, 0, v0
	v_mul_f32_e64 v0, |v0|, s18
	v_exp_f32_e32 v0, v0
	s_nop 0
	v_add_f32_e32 v0, 1.0, v0
	v_cmp_gt_f32_e32 vcc, s19, v0
	s_nop 1
	v_cndmask_b32_e64 v2, 0, 32, vcc
	v_ldexp_f32 v0, v0, v2
	v_log_f32_e32 v0, v0
	s_nop 0
	v_mul_f32_e32 v2, 0x3f317217, v0
	v_fma_f32 v2, v0, s21, -v2
	v_fmac_f32_e32 v2, 0x3377d1cf, v0
	v_fmac_f32_e32 v2, 0x3f317217, v0
	v_cmp_lt_f32_e64 s[90:91], |v0|, s22
	s_nop 1
	v_cndmask_b32_e64 v0, v0, v2, s[90:91]
	v_cndmask_b32_e32 v2, 0, v195, vcc
	v_sub_f32_e32 v0, v0, v2
	v_sub_f32_e32 v0, v1, v0
	v_fmac_f32_e32 v26, 0x3d800000, v0
	v_mov_b32_e32 v0, 0
	ds_write_b32 v95, v26 offset:1560
	ds_write_b32 v78, v26 offset:16640
	s_waitcnt lgkmcnt(0)
	s_barrier
	s_and_saveexec_b64 s[6:7], s[38:39]
	s_cbranch_execz .LBB0_776
	ds_read_b32 v0, v33 offset:16640
	s_waitcnt lgkmcnt(0)
	v_add_f32_e32 v0, 0, v0
	s_or_b64 exec, exec, s[6:7]
	s_and_saveexec_b64 s[6:7], s[40:41]
	s_cbranch_execnz .LBB0_777

.LBB0_842:
	s_bfe_u32 s11, s10, 0x20007
	s_lshl_b32 s12, s11, 6
	v_or_b32_e32 v0, s12, v196
	s_ashr_i32 s6, s10, 9
	v_lshlrev_b32_e32 v0, 2, v0
	v_mov_b32_e32 v1, v32
	s_ashr_i32 s7, s6, 31
	v_lshl_add_u64 v[2:3], s[58:59], 0, v[0:1]
	s_lshl_b64 s[82:83], s[6:7], 13
	s_and_b32 s6, s8, 0x1fc0
	v_add_co_u32_e32 v4, vcc, s20, v2
	s_or_b32 s82, s82, s6
	s_nop 0
	v_addc_co_u32_e32 v5, vcc, 0, v3, vcc
	s_movk_i32 s6, 0x2000
	v_add_co_u32_e32 v6, vcc, s6, v2
	s_movk_i32 s6, 0x3000
	s_nop 0
	v_addc_co_u32_e32 v7, vcc, 0, v3, vcc
	v_add_co_u32_e32 v2, vcc, s6, v2
	v_readlane_b32 s6, v252, 35
	s_nop 0
	v_addc_co_u32_e32 v3, vcc, 0, v3, vcc
	v_readlane_b32 s7, v252, 36
	global_load_dword v60, v0, s[58:59]
	global_load_dword v62, v0, s[58:59] offset:1024
	global_load_dword v59, v0, s[58:59] offset:2048
	global_load_dword v57, v0, s[58:59] offset:3072
	global_load_dword v61, v[6:7], off offset:-4096
	global_load_dword v58, v[4:5], off offset:1024
	global_load_dword v56, v[4:5], off offset:2048
	global_load_dword v47, v[4:5], off offset:3072
	global_load_dword v14, v[6:7], off
	global_load_dword v15, v[6:7], off offset:1024
	global_load_dword v13, v[6:7], off offset:2048
	global_load_dword v11, v[6:7], off offset:3072
	global_load_dword v12, v[2:3], off
	global_load_dword v10, v[2:3], off offset:1024
	global_load_dword v9, v[2:3], off offset:2048
	global_load_dword v8, v[2:3], off offset:3072
	global_load_dword v63, v0, s[0:1]
	v_lshl_add_u64 v[2:3], s[82:83], 0, v[18:19]
	v_mov_b64_e32 v[0:1], s[6:7]
	s_movk_i32 s13, 0x2cb0
	v_mad_u64_u32 v[4:5], s[6:7], v2, s13, v[0:1]
	v_mad_i32_i24 v5, v3, s13, v5
	v_add_co_u32_e32 v2, vcc, s20, v4
	s_mov_b64 s[18:19], 0x1c90
	s_nop 0
	v_addc_co_u32_e32 v3, vcc, 0, v5, vcc
	v_lshl_add_u64 v[6:7], v[4:5], 0, s[18:19]
	v_lshl_add_u64 v[172:173], s[82:83], 0, v[18:19]
	v_mad_u64_u32 v[174:175], s[6:7], v172, s13, v[0:1]
	v_mad_i32_i24 v175, v173, s13, v175
	v_lshl_add_u64 v[174:175], v[174:175], 0, s[18:19]
	global_load_dwordx4 v[198:201], v[174:175], off
	global_load_dwordx4 v[202:205], v[174:175], off offset:16
	v_lshl_add_u64 v[176:177], s[82:83], 0, v[20:21]
	v_mad_u64_u32 v[178:179], s[6:7], v176, s13, v[0:1]
	v_mad_i32_i24 v179, v177, s13, v179
	v_lshl_add_u64 v[178:179], v[178:179], 0, s[18:19]
	global_load_dwordx4 v[206:209], v[178:179], off
	global_load_dwordx4 v[210:213], v[178:179], off offset:16
	v_lshl_add_u64 v[172:173], s[82:83], 0, v[22:23]
	v_mad_u64_u32 v[174:175], s[6:7], v172, s13, v[0:1]
	v_mad_i32_i24 v175, v173, s13, v175
	v_lshl_add_u64 v[174:175], v[174:175], 0, s[18:19]
	global_load_dwordx4 v[214:217], v[174:175], off
	global_load_dwordx4 v[218:221], v[174:175], off offset:16
	v_lshl_add_u64 v[176:177], s[82:83], 0, v[24:25]
	v_mad_u64_u32 v[178:179], s[6:7], v176, s13, v[0:1]
	v_mad_i32_i24 v179, v177, s13, v179
	v_lshl_add_u64 v[178:179], v[178:179], 0, s[18:19]
	global_load_dwordx4 v[222:225], v[178:179], off
	global_load_dwordx4 v[226:229], v[178:179], off offset:16
	v_lshl_add_u64 v[172:173], s[82:83], 0, v[26:27]
	v_mad_u64_u32 v[174:175], s[6:7], v172, s13, v[0:1]
	v_mad_i32_i24 v175, v173, s13, v175
	v_lshl_add_u64 v[174:175], v[174:175], 0, s[18:19]
	global_load_dwordx4 v[230:233], v[174:175], off
	global_load_dwordx4 v[234:237], v[174:175], off offset:16
	v_lshl_add_u64 v[176:177], s[82:83], 0, v[28:29]
	v_mad_u64_u32 v[178:179], s[6:7], v176, s13, v[0:1]
	v_mad_i32_i24 v179, v177, s13, v179
	v_lshl_add_u64 v[178:179], v[178:179], 0, s[18:19]
	global_load_dwordx4 v[238:241], v[178:179], off
	global_load_dwordx4 v[242:245], v[178:179], off offset:16
	v_lshl_add_u64 v[172:173], s[82:83], 0, v[30:31]
	v_mad_u64_u32 v[174:175], s[6:7], v172, s13, v[0:1]
	v_mad_i32_i24 v175, v173, s13, v175
	v_lshl_add_u64 v[174:175], v[174:175], 0, s[18:19]
	global_load_dwordx4 v[246:249], v[174:175], off
	global_load_dwordx4 v[160:163], v[174:175], off offset:16
	v_lshl_add_u64 v[176:177], s[82:83], 0, v[34:35]
	v_mad_u64_u32 v[178:179], s[6:7], v176, s13, v[0:1]
	v_mad_i32_i24 v179, v177, s13, v179
	v_lshl_add_u64 v[178:179], v[178:179], 0, s[18:19]
	global_load_dwordx4 v[164:167], v[178:179], off
	global_load_dwordx4 v[168:171], v[178:179], off offset:16
	s_waitcnt vmcnt(0)
	v_mov_b64_e32 v[2:3], v[198:199]
	v_mov_b64_e32 v[4:5], v[200:201]
	s_nop 0
	v_mov_b64_e32 v[70:71], v[202:203]
	v_mov_b64_e32 v[72:73], v[204:205]
	s_mov_b32 s14, 0xbfb8aa3b
	s_mov_b32 s15, 0x800000
	s_mov_b32 s16, 0x3f317217
	s_mov_b32 s17, 0x7f800000
	s_mov_b32 s6, 0x3d800000
	s_waitcnt vmcnt(0)
	v_lshlrev_b32_e32 v6, 16, v2
	v_and_b32_e32 v2, 0xffff0000, v2
	v_mul_f32_e32 v2, v62, v2
	v_fmac_f32_e32 v2, v60, v6
	v_lshlrev_b32_e32 v6, 16, v3
	v_fmac_f32_e32 v2, v59, v6
	v_and_b32_e32 v3, 0xffff0000, v3
	v_fmac_f32_e32 v2, v57, v3
	v_lshlrev_b32_e32 v3, 16, v4
	v_fmac_f32_e32 v2, v61, v3
	v_and_b32_e32 v3, 0xffff0000, v4
	v_fmac_f32_e32 v2, v58, v3
	v_lshlrev_b32_e32 v3, 16, v5
	v_fmac_f32_e32 v2, v56, v3
	v_and_b32_e32 v3, 0xffff0000, v5
	v_and_b32_e32 v4, 0xffff0000, v70
	v_fmac_f32_e32 v2, v47, v3
	v_lshlrev_b32_e32 v3, 16, v70
	v_mul_f32_e32 v4, v15, v4
	v_fmac_f32_e32 v4, v14, v3
	v_lshlrev_b32_e32 v3, 16, v71
	v_fmac_f32_e32 v4, v13, v3
	v_and_b32_e32 v3, 0xffff0000, v71
	v_fmac_f32_e32 v4, v11, v3
	v_lshlrev_b32_e32 v3, 16, v72
	v_fmac_f32_e32 v4, v12, v3
	v_and_b32_e32 v3, 0xffff0000, v72
	v_fmac_f32_e32 v4, v10, v3
	v_lshlrev_b32_e32 v3, 16, v73
	v_fmac_f32_e32 v4, v9, v3
	v_and_b32_e32 v3, 0xffff0000, v73
	v_add_f32_e32 v2, v63, v2
	v_fmac_f32_e32 v4, v8, v3
	v_add_f32_e32 v2, v2, v4
	v_min_f32_e32 v3, 0, v2
	v_mul_f32_e64 v2, |v2|, s14
	v_exp_f32_e32 v2, v2
	s_nop 0
	v_add_f32_e32 v2, 1.0, v2
	v_cmp_gt_f32_e32 vcc, s15, v2
	s_nop 1
	v_cndmask_b32_e64 v4, 0, 32, vcc
	v_ldexp_f32 v2, v2, v4
	v_log_f32_e32 v2, v2
	s_nop 0
	v_mul_f32_e32 v4, 0x3f317217, v2
	v_fma_f32 v4, v2, s16, -v4
	v_fmac_f32_e32 v4, 0x3377d1cf, v2
	v_fmac_f32_e32 v4, 0x3f317217, v2
	v_cmp_lt_f32_e64 s[56:57], |v2|, s17
	s_nop 1
	v_cndmask_b32_e64 v2, v2, v4, s[56:57]
	v_cndmask_b32_e32 v4, 0, v195, vcc
	v_sub_f32_e32 v2, v2, v4
	v_sub_f32_e32 v2, v3, v2
	v_lshl_add_u64 v[4:5], s[82:83], 0, v[20:21]
	v_fma_f32 v3, v2, s6, 0
	v_mad_u64_u32 v[6:7], s[6:7], v4, s13, v[0:1]
	v_mad_i32_i24 v7, v5, s13, v7
	v_add_co_u32_e32 v4, vcc, s20, v6
	ds_write_b32 v54, v3
	s_nop 0
	v_addc_co_u32_e32 v5, vcc, 0, v7, vcc
	v_lshl_add_u64 v[64:65], v[6:7], 0, s[18:19]
	v_mov_b64_e32 v[4:5], v[206:207]
	v_mov_b64_e32 v[6:7], v[208:209]
	s_nop 0
	v_mov_b64_e32 v[70:71], v[210:211]
	v_mov_b64_e32 v[72:73], v[212:213]
	s_waitcnt vmcnt(1)
	v_lshlrev_b32_e32 v2, 16, v4
	v_and_b32_e32 v4, 0xffff0000, v4
	v_mul_f32_e32 v4, v62, v4
	v_fmac_f32_e32 v4, v60, v2
	v_lshlrev_b32_e32 v2, 16, v5
	v_fmac_f32_e32 v4, v59, v2
	v_and_b32_e32 v2, 0xffff0000, v5
	v_fmac_f32_e32 v4, v57, v2
	v_lshlrev_b32_e32 v2, 16, v6
	v_fmac_f32_e32 v4, v61, v2
	v_and_b32_e32 v2, 0xffff0000, v6
	v_fmac_f32_e32 v4, v58, v2
	v_lshlrev_b32_e32 v2, 16, v7
	v_fmac_f32_e32 v4, v56, v2
	v_and_b32_e32 v2, 0xffff0000, v7
	v_fmac_f32_e32 v4, v47, v2
	s_waitcnt vmcnt(0)
	v_and_b32_e32 v5, 0xffff0000, v70
	v_add_f32_e32 v2, v63, v4
	v_lshlrev_b32_e32 v4, 16, v70
	v_mul_f32_e32 v5, v15, v5
	v_fmac_f32_e32 v5, v14, v4
	v_lshlrev_b32_e32 v4, 16, v71
	v_fmac_f32_e32 v5, v13, v4
	v_and_b32_e32 v4, 0xffff0000, v71
	v_fmac_f32_e32 v5, v11, v4
	v_lshlrev_b32_e32 v4, 16, v72
	v_fmac_f32_e32 v5, v12, v4
	v_and_b32_e32 v4, 0xffff0000, v72
	v_fmac_f32_e32 v5, v10, v4
	v_lshlrev_b32_e32 v4, 16, v73
	v_fmac_f32_e32 v5, v9, v4
	v_and_b32_e32 v4, 0xffff0000, v73
	v_fmac_f32_e32 v5, v8, v4
	v_add_f32_e32 v2, v2, v5
	v_min_f32_e32 v4, 0, v2
	v_mul_f32_e64 v2, |v2|, s14
	v_exp_f32_e32 v2, v2
	s_nop 0
	v_add_f32_e32 v2, 1.0, v2
	v_cmp_gt_f32_e32 vcc, s15, v2
	s_nop 1
	v_cndmask_b32_e64 v5, 0, 32, vcc
	v_ldexp_f32 v2, v2, v5
	v_log_f32_e32 v2, v2
	s_nop 0
	v_mul_f32_e32 v5, 0x3f317217, v2
	v_fma_f32 v5, v2, s16, -v5
	v_fmac_f32_e32 v5, 0x3377d1cf, v2
	v_fmac_f32_e32 v5, 0x3f317217, v2
	v_cmp_lt_f32_e64 s[56:57], |v2|, s17
	s_nop 1
	v_cndmask_b32_e64 v2, v2, v5, s[56:57]
	v_cndmask_b32_e32 v5, 0, v195, vcc
	v_sub_f32_e32 v2, v2, v5
	v_sub_f32_e32 v2, v4, v2
	v_lshl_add_u64 v[4:5], s[82:83], 0, v[22:23]
	v_mad_u64_u32 v[6:7], s[6:7], v4, s13, v[0:1]
	v_mad_i32_i24 v7, v5, s13, v7
	v_add_co_u32_e32 v4, vcc, s20, v6
	v_lshl_add_u64 v[64:65], v[6:7], 0, s[18:19]
	s_nop 0
	v_addc_co_u32_e32 v5, vcc, 0, v7, vcc
	v_mov_b64_e32 v[4:5], v[214:215]
	v_mov_b64_e32 v[6:7], v[216:217]
	s_nop 0
	v_mov_b64_e32 v[70:71], v[218:219]
	v_mov_b64_e32 v[72:73], v[220:221]
	v_fmac_f32_e32 v3, 0x3d800000, v2
	s_waitcnt vmcnt(1)
	v_lshlrev_b32_e32 v2, 16, v4
	v_and_b32_e32 v4, 0xffff0000, v4
	v_mul_f32_e32 v4, v62, v4
	v_fmac_f32_e32 v4, v60, v2
	v_lshlrev_b32_e32 v2, 16, v5
	v_fmac_f32_e32 v4, v59, v2
	v_and_b32_e32 v2, 0xffff0000, v5
	v_fmac_f32_e32 v4, v57, v2
	v_lshlrev_b32_e32 v2, 16, v6
	v_fmac_f32_e32 v4, v61, v2
	v_and_b32_e32 v2, 0xffff0000, v6
	v_fmac_f32_e32 v4, v58, v2
	v_lshlrev_b32_e32 v2, 16, v7
	v_fmac_f32_e32 v4, v56, v2
	v_and_b32_e32 v2, 0xffff0000, v7
	v_fmac_f32_e32 v4, v47, v2
	s_waitcnt vmcnt(0)
	v_and_b32_e32 v5, 0xffff0000, v70
	v_add_f32_e32 v2, v63, v4
	v_lshlrev_b32_e32 v4, 16, v70
	v_mul_f32_e32 v5, v15, v5
	v_fmac_f32_e32 v5, v14, v4
	v_lshlrev_b32_e32 v4, 16, v71
	v_fmac_f32_e32 v5, v13, v4
	v_and_b32_e32 v4, 0xffff0000, v71
	v_fmac_f32_e32 v5, v11, v4
	v_lshlrev_b32_e32 v4, 16, v72
	v_fmac_f32_e32 v5, v12, v4
	v_and_b32_e32 v4, 0xffff0000, v72
	v_fmac_f32_e32 v5, v10, v4
	v_lshlrev_b32_e32 v4, 16, v73
	v_fmac_f32_e32 v5, v9, v4
	v_and_b32_e32 v4, 0xffff0000, v73
	v_fmac_f32_e32 v5, v8, v4
	v_add_f32_e32 v2, v2, v5
	v_min_f32_e32 v4, 0, v2
	v_mul_f32_e64 v2, |v2|, s14
	v_exp_f32_e32 v2, v2
	s_nop 0
	v_add_f32_e32 v2, 1.0, v2
	v_cmp_gt_f32_e32 vcc, s15, v2
	s_nop 1
	v_cndmask_b32_e64 v5, 0, 32, vcc
	v_ldexp_f32 v2, v2, v5
	v_log_f32_e32 v2, v2
	s_nop 0
	v_mul_f32_e32 v5, 0x3f317217, v2
	v_fma_f32 v5, v2, s16, -v5
	v_fmac_f32_e32 v5, 0x3377d1cf, v2
	v_fmac_f32_e32 v5, 0x3f317217, v2
	v_cmp_lt_f32_e64 s[56:57], |v2|, s17
	s_nop 1
	v_cndmask_b32_e64 v2, v2, v5, s[56:57]
	v_cndmask_b32_e32 v5, 0, v195, vcc
	v_sub_f32_e32 v2, v2, v5
	v_sub_f32_e32 v2, v4, v2
	v_lshl_add_u64 v[4:5], s[82:83], 0, v[24:25]
	v_mad_u64_u32 v[6:7], s[6:7], v4, s13, v[0:1]
	v_fmamk_f32 v2, v2, 0x3d800000, v3
	v_mad_i32_i24 v7, v5, s13, v7
	v_add_co_u32_e32 v4, vcc, s20, v6
	ds_write2_b32 v55, v3, v2 offset1:65
	s_nop 0
	v_addc_co_u32_e32 v5, vcc, 0, v7, vcc
	v_lshl_add_u64 v[64:65], v[6:7], 0, s[18:19]
	v_mov_b64_e32 v[4:5], v[222:223]
	v_mov_b64_e32 v[6:7], v[224:225]
	s_nop 0
	v_mov_b64_e32 v[70:71], v[226:227]
	v_mov_b64_e32 v[72:73], v[228:229]
	s_waitcnt vmcnt(1)
	v_lshlrev_b32_e32 v3, 16, v4
	v_and_b32_e32 v4, 0xffff0000, v4
	v_mul_f32_e32 v4, v62, v4
	v_fmac_f32_e32 v4, v60, v3
	v_lshlrev_b32_e32 v3, 16, v5
	v_fmac_f32_e32 v4, v59, v3
	v_and_b32_e32 v3, 0xffff0000, v5
	v_fmac_f32_e32 v4, v57, v3
	v_lshlrev_b32_e32 v3, 16, v6
	v_fmac_f32_e32 v4, v61, v3
	v_and_b32_e32 v3, 0xffff0000, v6
	v_fmac_f32_e32 v4, v58, v3
	v_lshlrev_b32_e32 v3, 16, v7
	v_fmac_f32_e32 v4, v56, v3
	v_and_b32_e32 v3, 0xffff0000, v7
	v_fmac_f32_e32 v4, v47, v3
	s_waitcnt vmcnt(0)
	v_and_b32_e32 v5, 0xffff0000, v70
	v_add_f32_e32 v3, v63, v4
	v_lshlrev_b32_e32 v4, 16, v70
	v_mul_f32_e32 v5, v15, v5
	v_fmac_f32_e32 v5, v14, v4
	v_lshlrev_b32_e32 v4, 16, v71
	v_fmac_f32_e32 v5, v13, v4
	v_and_b32_e32 v4, 0xffff0000, v71
	v_fmac_f32_e32 v5, v11, v4
	v_lshlrev_b32_e32 v4, 16, v72
	v_fmac_f32_e32 v5, v12, v4
	v_and_b32_e32 v4, 0xffff0000, v72
	v_fmac_f32_e32 v5, v10, v4
	v_lshlrev_b32_e32 v4, 16, v73
	v_fmac_f32_e32 v5, v9, v4
	v_and_b32_e32 v4, 0xffff0000, v73
	v_fmac_f32_e32 v5, v8, v4
	v_add_f32_e32 v3, v3, v5
	v_min_f32_e32 v4, 0, v3
	v_mul_f32_e64 v3, |v3|, s14
	v_exp_f32_e32 v3, v3
	s_nop 0
	v_add_f32_e32 v3, 1.0, v3
	v_cmp_gt_f32_e32 vcc, s15, v3
	s_nop 1
	v_cndmask_b32_e64 v5, 0, 32, vcc
	v_ldexp_f32 v3, v3, v5
	v_log_f32_e32 v3, v3
	s_nop 0
	v_mul_f32_e32 v5, 0x3f317217, v3
	v_fma_f32 v5, v3, s16, -v5
	v_fmac_f32_e32 v5, 0x3377d1cf, v3
	v_fmac_f32_e32 v5, 0x3f317217, v3
	v_cmp_lt_f32_e64 s[56:57], |v3|, s17
	s_nop 1
	v_cndmask_b32_e64 v3, v3, v5, s[56:57]
	v_cndmask_b32_e32 v5, 0, v195, vcc
	v_sub_f32_e32 v3, v3, v5
	v_sub_f32_e32 v3, v4, v3
	v_lshl_add_u64 v[4:5], s[82:83], 0, v[26:27]
	v_mad_u64_u32 v[6:7], s[6:7], v4, s13, v[0:1]
	v_mad_i32_i24 v7, v5, s13, v7
	v_add_co_u32_e32 v4, vcc, s20, v6
	v_lshl_add_u64 v[64:65], v[6:7], 0, s[18:19]
	s_nop 0
	v_addc_co_u32_e32 v5, vcc, 0, v7, vcc
	v_mov_b64_e32 v[4:5], v[230:231]
	v_mov_b64_e32 v[6:7], v[232:233]
	s_nop 0
	v_mov_b64_e32 v[70:71], v[234:235]
	v_mov_b64_e32 v[72:73], v[236:237]
	v_fmac_f32_e32 v2, 0x3d800000, v3
	s_waitcnt vmcnt(1)
	v_lshlrev_b32_e32 v3, 16, v4
	v_and_b32_e32 v4, 0xffff0000, v4
	v_mul_f32_e32 v4, v62, v4
	v_fmac_f32_e32 v4, v60, v3
	v_lshlrev_b32_e32 v3, 16, v5
	v_fmac_f32_e32 v4, v59, v3
	v_and_b32_e32 v3, 0xffff0000, v5
	v_fmac_f32_e32 v4, v57, v3
	v_lshlrev_b32_e32 v3, 16, v6
	v_fmac_f32_e32 v4, v61, v3
	v_and_b32_e32 v3, 0xffff0000, v6
	v_fmac_f32_e32 v4, v58, v3
	v_lshlrev_b32_e32 v3, 16, v7
	v_fmac_f32_e32 v4, v56, v3
	v_and_b32_e32 v3, 0xffff0000, v7
	v_fmac_f32_e32 v4, v47, v3
	s_waitcnt vmcnt(0)
	v_and_b32_e32 v5, 0xffff0000, v70
	v_add_f32_e32 v3, v63, v4
	v_lshlrev_b32_e32 v4, 16, v70
	v_mul_f32_e32 v5, v15, v5
	v_fmac_f32_e32 v5, v14, v4
	v_lshlrev_b32_e32 v4, 16, v71
	v_fmac_f32_e32 v5, v13, v4
	v_and_b32_e32 v4, 0xffff0000, v71
	v_fmac_f32_e32 v5, v11, v4
	v_lshlrev_b32_e32 v4, 16, v72
	v_fmac_f32_e32 v5, v12, v4
	v_and_b32_e32 v4, 0xffff0000, v72
	v_fmac_f32_e32 v5, v10, v4
	v_lshlrev_b32_e32 v4, 16, v73
	v_fmac_f32_e32 v5, v9, v4
	v_and_b32_e32 v4, 0xffff0000, v73
	v_fmac_f32_e32 v5, v8, v4
	v_add_f32_e32 v3, v3, v5
	v_min_f32_e32 v4, 0, v3
	v_mul_f32_e64 v3, |v3|, s14
	v_exp_f32_e32 v3, v3
	s_nop 0
	v_add_f32_e32 v3, 1.0, v3
	v_cmp_gt_f32_e32 vcc, s15, v3
	s_nop 1
	v_cndmask_b32_e64 v5, 0, 32, vcc
	v_ldexp_f32 v3, v3, v5
	v_log_f32_e32 v3, v3
	s_nop 0
	v_mul_f32_e32 v5, 0x3f317217, v3
	v_fma_f32 v5, v3, s16, -v5
	v_fmac_f32_e32 v5, 0x3377d1cf, v3
	v_fmac_f32_e32 v5, 0x3f317217, v3
	v_cmp_lt_f32_e64 s[56:57], |v3|, s17
	s_nop 1
	v_cndmask_b32_e64 v3, v3, v5, s[56:57]
	v_cndmask_b32_e32 v5, 0, v195, vcc
	v_sub_f32_e32 v3, v3, v5
	v_sub_f32_e32 v3, v4, v3
	v_lshl_add_u64 v[4:5], s[82:83], 0, v[28:29]
	v_mad_u64_u32 v[6:7], s[6:7], v4, s13, v[0:1]
	v_fmamk_f32 v3, v3, 0x3d800000, v2
	v_mad_i32_i24 v7, v5, s13, v7
	v_add_co_u32_e32 v4, vcc, s20, v6
	ds_write2_b32 v55, v2, v3 offset0:130 offset1:195
	s_nop 0
	v_addc_co_u32_e32 v5, vcc, 0, v7, vcc
	v_lshl_add_u64 v[64:65], v[6:7], 0, s[18:19]
	v_mov_b64_e32 v[4:5], v[238:239]
	v_mov_b64_e32 v[6:7], v[240:241]
	s_nop 0
	v_mov_b64_e32 v[70:71], v[242:243]
	v_mov_b64_e32 v[72:73], v[244:245]
	s_waitcnt vmcnt(1)
	v_lshlrev_b32_e32 v2, 16, v4
	v_and_b32_e32 v4, 0xffff0000, v4
	v_mul_f32_e32 v4, v62, v4
	v_fmac_f32_e32 v4, v60, v2
	v_lshlrev_b32_e32 v2, 16, v5
	v_fmac_f32_e32 v4, v59, v2
	v_and_b32_e32 v2, 0xffff0000, v5
	v_fmac_f32_e32 v4, v57, v2
	v_lshlrev_b32_e32 v2, 16, v6
	v_fmac_f32_e32 v4, v61, v2
	v_and_b32_e32 v2, 0xffff0000, v6
	v_fmac_f32_e32 v4, v58, v2
	v_lshlrev_b32_e32 v2, 16, v7
	v_fmac_f32_e32 v4, v56, v2
	v_and_b32_e32 v2, 0xffff0000, v7
	v_fmac_f32_e32 v4, v47, v2
	s_waitcnt vmcnt(0)
	v_and_b32_e32 v5, 0xffff0000, v70
	v_add_f32_e32 v2, v63, v4
	v_lshlrev_b32_e32 v4, 16, v70
	v_mul_f32_e32 v5, v15, v5
	v_fmac_f32_e32 v5, v14, v4
	v_lshlrev_b32_e32 v4, 16, v71
	v_fmac_f32_e32 v5, v13, v4
	v_and_b32_e32 v4, 0xffff0000, v71
	v_fmac_f32_e32 v5, v11, v4
	v_lshlrev_b32_e32 v4, 16, v72
	v_fmac_f32_e32 v5, v12, v4
	v_and_b32_e32 v4, 0xffff0000, v72
	v_fmac_f32_e32 v5, v10, v4
	v_lshlrev_b32_e32 v4, 16, v73
	v_fmac_f32_e32 v5, v9, v4
	v_and_b32_e32 v4, 0xffff0000, v73
	v_fmac_f32_e32 v5, v8, v4
	v_add_f32_e32 v2, v2, v5
	v_min_f32_e32 v4, 0, v2
	v_mul_f32_e64 v2, |v2|, s14
	v_exp_f32_e32 v2, v2
	s_nop 0
	v_add_f32_e32 v2, 1.0, v2
	v_cmp_gt_f32_e32 vcc, s15, v2
	s_nop 1
	v_cndmask_b32_e64 v5, 0, 32, vcc
	v_ldexp_f32 v2, v2, v5
	v_log_f32_e32 v2, v2
	s_nop 0
	v_mul_f32_e32 v5, 0x3f317217, v2
	v_fma_f32 v5, v2, s16, -v5
	v_fmac_f32_e32 v5, 0x3377d1cf, v2
	v_fmac_f32_e32 v5, 0x3f317217, v2
	v_cmp_lt_f32_e64 s[56:57], |v2|, s17
	s_nop 1
	v_cndmask_b32_e64 v2, v2, v5, s[56:57]
	v_cndmask_b32_e32 v5, 0, v195, vcc
	v_sub_f32_e32 v2, v2, v5
	v_sub_f32_e32 v2, v4, v2
	v_lshl_add_u64 v[4:5], s[82:83], 0, v[30:31]
	v_mad_u64_u32 v[6:7], s[6:7], v4, s13, v[0:1]
	v_mad_i32_i24 v7, v5, s13, v7
	v_add_co_u32_e32 v4, vcc, s20, v6
	v_lshl_add_u64 v[64:65], v[6:7], 0, s[18:19]
	s_nop 0
	v_addc_co_u32_e32 v5, vcc, 0, v7, vcc
	v_mov_b64_e32 v[4:5], v[246:247]
	v_mov_b64_e32 v[6:7], v[248:249]
	s_nop 0
	v_mov_b64_e32 v[70:71], v[160:161]
	v_mov_b64_e32 v[72:73], v[162:163]
	v_fmac_f32_e32 v3, 0x3d800000, v2
	v_add_u32_e32 v64, 0x400, v55
	s_waitcnt vmcnt(1)
	v_lshlrev_b32_e32 v2, 16, v4
	v_and_b32_e32 v4, 0xffff0000, v4
	v_mul_f32_e32 v4, v62, v4
	v_fmac_f32_e32 v4, v60, v2
	v_lshlrev_b32_e32 v2, 16, v5
	v_fmac_f32_e32 v4, v59, v2
	v_and_b32_e32 v2, 0xffff0000, v5
	v_fmac_f32_e32 v4, v57, v2
	v_lshlrev_b32_e32 v2, 16, v6
	v_fmac_f32_e32 v4, v61, v2
	v_and_b32_e32 v2, 0xffff0000, v6
	v_fmac_f32_e32 v4, v58, v2
	v_lshlrev_b32_e32 v2, 16, v7
	v_fmac_f32_e32 v4, v56, v2
	v_and_b32_e32 v2, 0xffff0000, v7
	v_fmac_f32_e32 v4, v47, v2
	s_waitcnt vmcnt(0)
	v_and_b32_e32 v5, 0xffff0000, v70
	v_add_f32_e32 v2, v63, v4
	v_lshlrev_b32_e32 v4, 16, v70
	v_mul_f32_e32 v5, v15, v5
	v_fmac_f32_e32 v5, v14, v4
	v_lshlrev_b32_e32 v4, 16, v71
	v_fmac_f32_e32 v5, v13, v4
	v_and_b32_e32 v4, 0xffff0000, v71
	v_fmac_f32_e32 v5, v11, v4
	v_lshlrev_b32_e32 v4, 16, v72
	v_fmac_f32_e32 v5, v12, v4
	v_and_b32_e32 v4, 0xffff0000, v72
	v_fmac_f32_e32 v5, v10, v4
	v_lshlrev_b32_e32 v4, 16, v73
	v_fmac_f32_e32 v5, v9, v4
	v_and_b32_e32 v4, 0xffff0000, v73
	v_fmac_f32_e32 v5, v8, v4
	v_add_f32_e32 v2, v2, v5
	v_min_f32_e32 v4, 0, v2
	v_mul_f32_e64 v2, |v2|, s14
	v_exp_f32_e32 v2, v2
	s_nop 0
	v_add_f32_e32 v2, 1.0, v2
	v_cmp_gt_f32_e32 vcc, s15, v2
	s_nop 1
	v_cndmask_b32_e64 v5, 0, 32, vcc
	v_ldexp_f32 v2, v2, v5
	v_log_f32_e32 v2, v2
	s_nop 0
	v_mul_f32_e32 v5, 0x3f317217, v2
	v_fma_f32 v5, v2, s16, -v5
	v_fmac_f32_e32 v5, 0x3377d1cf, v2
	v_fmac_f32_e32 v5, 0x3f317217, v2
	v_cmp_lt_f32_e64 s[56:57], |v2|, s17
	s_nop 1
	v_cndmask_b32_e64 v2, v2, v5, s[56:57]
	v_cndmask_b32_e32 v5, 0, v195, vcc
	v_sub_f32_e32 v2, v2, v5
	v_sub_f32_e32 v2, v4, v2
	v_fmamk_f32 v65, v2, 0x3d800000, v3
	ds_write2_b32 v64, v3, v65 offset0:4 offset1:69
	v_lshl_add_u64 v[2:3], s[82:83], 0, v[34:35]
	v_mad_u64_u32 v[0:1], s[6:7], v2, s13, v[0:1]
	v_mad_i32_i24 v1, v3, s13, v1
	v_lshl_add_u64 v[4:5], v[0:1], 0, s[18:19]
	v_add_co_u32_e32 v0, vcc, s20, v0
	s_nop 1
	v_addc_co_u32_e32 v1, vcc, 0, v1, vcc
	v_mov_b64_e32 v[0:1], v[164:165]
	v_mov_b64_e32 v[2:3], v[166:167]
	s_nop 0
	v_mov_b64_e32 v[4:5], v[168:169]
	v_mov_b64_e32 v[6:7], v[170:171]
	s_waitcnt vmcnt(1)
	v_lshlrev_b32_e32 v70, 16, v0
	v_and_b32_e32 v0, 0xffff0000, v0
	v_mul_f32_e32 v0, v62, v0
	v_fmac_f32_e32 v0, v60, v70
	v_lshlrev_b32_e32 v60, 16, v1
	v_fmac_f32_e32 v0, v59, v60
	v_and_b32_e32 v1, 0xffff0000, v1
	v_fmac_f32_e32 v0, v57, v1
	v_lshlrev_b32_e32 v1, 16, v2
	v_fmac_f32_e32 v0, v61, v1
	v_and_b32_e32 v1, 0xffff0000, v2
	v_fmac_f32_e32 v0, v58, v1
	v_lshlrev_b32_e32 v1, 16, v3
	v_fmac_f32_e32 v0, v56, v1
	v_and_b32_e32 v1, 0xffff0000, v3
	s_waitcnt vmcnt(0)
	v_and_b32_e32 v2, 0xffff0000, v4
	v_fmac_f32_e32 v0, v47, v1
	v_lshlrev_b32_e32 v1, 16, v4
	v_mul_f32_e32 v2, v15, v2
	v_fmac_f32_e32 v2, v14, v1
	v_lshlrev_b32_e32 v1, 16, v5
	v_fmac_f32_e32 v2, v13, v1
	v_and_b32_e32 v1, 0xffff0000, v5
	v_fmac_f32_e32 v2, v11, v1
	v_lshlrev_b32_e32 v1, 16, v6
	v_fmac_f32_e32 v2, v12, v1
	v_and_b32_e32 v1, 0xffff0000, v6
	v_fmac_f32_e32 v2, v10, v1
	v_lshlrev_b32_e32 v1, 16, v7
	v_fmac_f32_e32 v2, v9, v1
	v_and_b32_e32 v1, 0xffff0000, v7
	v_add_f32_e32 v0, v63, v0
	v_fmac_f32_e32 v2, v8, v1
	v_add_f32_e32 v0, v0, v2
	v_min_f32_e32 v1, 0, v0
	v_mul_f32_e64 v0, |v0|, s14
	v_exp_f32_e32 v0, v0
	s_nop 0
	v_add_f32_e32 v0, 1.0, v0
	v_cmp_gt_f32_e32 vcc, s15, v0
	s_nop 1
	v_cndmask_b32_e64 v2, 0, 32, vcc
	v_ldexp_f32 v0, v0, v2
	v_log_f32_e32 v0, v0
	s_nop 0
	v_mul_f32_e32 v2, 0x3f317217, v0
	v_fma_f32 v2, v0, s16, -v2
	v_fmac_f32_e32 v2, 0x3377d1cf, v0
	v_fmac_f32_e32 v2, 0x3f317217, v0
	v_cmp_lt_f32_e64 s[56:57], |v0|, s17
	s_nop 1
	v_cndmask_b32_e64 v0, v0, v2, s[56:57]
	v_cndmask_b32_e32 v2, 0, v195, vcc
	v_sub_f32_e32 v0, v0, v2
	v_sub_f32_e32 v0, v1, v0
	v_fmac_f32_e32 v65, 0x3d800000, v0
	v_mov_b32_e32 v0, 0
	ds_write_b32 v55, v65 offset:1560
	ds_write_b32 v41, v65 offset:16640
	s_waitcnt lgkmcnt(0)
	s_barrier
	s_and_saveexec_b64 s[6:7], s[38:39]
	s_cbranch_execz .LBB0_850
	ds_read_b32 v0, v37 offset:16640
	s_waitcnt lgkmcnt(0)
	v_add_f32_e32 v0, 0, v0
	s_or_b64 exec, exec, s[6:7]
	s_and_saveexec_b64 s[6:7], s[40:41]
	s_cbranch_execnz .LBB0_851
